# plus hand-written phase_yc_fixup with dwordx4 loads and wave-uniform scalar row addressing
# speedup vs baseline: 1.0421x; 1.0098x over previous
.LBB0_909:
	s_or_b64 exec, exec, s[36:37]
	s_mov_b64 s[12:13], s[0:1]
	s_mov_b64 s[10:11], s[0:1]
	s_mov_b64 s[6:7], s[0:1]
	s_mov_b64 s[4:5], s[0:1]
	v_mov_b32_e32 v0, v219
	v_readlane_b32 s2, v253, 49
	s_barrier
	s_mov_b64 s[8:9], exec
	v_readlane_b32 s2, v253, 49
	v_readfirstlane_b32 s3, v219
	v_and_b32_e32 v12, 0x7f, v219
	s_add_u32 s2, s2, s3
	s_cmp_lt_u32 s2, 0x9100
	s_cbranch_scc0 .Lycx_skip
	s_load_dwordx2 s[6:7], s[0:1], 0xb0
	s_load_dwordx2 s[10:11], s[0:1], 0x58
	s_load_dwordx2 s[24:25], s[0:1], 0x28
	v_lshlrev_b32_e32 v14, 4, v12
	v_lshlrev_b32_e32 v12, 5, v12
	v_add_u32_e32 v13, 0x1000, v12
	s_lshr_b32 s4, s2, 7
	s_lshr_b32 s31, s4, 1
	s_and_b32 s32, s4, 1
	s_cmp_lt_u32 s4, 0x100
	s_cbranch_scc0 .Lycx_hi
	s_lshl_b32 s29, s31, 6
	s_add_u32 s29, s29, s32
	s_branch .Lycx_row

.Lycx_row:
	s_lshl_b64 s[34:35], s[64:65], 2
	s_lshl_b32 s5, s60, 17
	s_waitcnt lgkmcnt(0)
	s_add_u32 s10, s10, s34
	s_addc_u32 s11, s11, s35
	s_add_u32 s24, s24, s5
	s_addc_u32 s25, s25, 0
	s_add_u32 s36, s6, 0x35a00000
	s_addc_u32 s37, s7, 0
	s_add_u32 s6, s6, 0x18f00000
	s_addc_u32 s7, s7, 0
	s_add_u32 s38, s10, 0x1000
	s_addc_u32 s39, s11, 0
	s_add_u32 s42, s10, 0x2000
	s_addc_u32 s43, s11, 0
	global_load_dwordx4 v[132:135], v12, s[10:11]
	global_load_dwordx4 v[136:139], v12, s[10:11] offset:16
	global_load_dwordx4 v[140:143], v12, s[38:39]
	global_load_dwordx4 v[144:147], v12, s[38:39] offset:16
	global_load_dwordx4 v[148:151], v12, s[42:43]
	global_load_dwordx4 v[152:155], v12, s[42:43] offset:16
	s_lshr_b32 s62, s29, 6
	s_lshl_b32 s62, s62, 2
	s_sub_u32 s63, s29, 0x2000
	s_lshr_b32 s63, s63, 4
	s_lshl_b32 s63, s63, 2
	s_add_u32 s63, s63, 0x200
	s_cmp_lt_u32 s29, 0x2000
	s_cselect_b32 s62, s62, s63
	s_add_u32 s63, s29, 2
	s_and_b32 s63, s63, 3
	s_add_u32 s62, s62, s63
	s_lshl_b32 s62, s62, 13
	s_add_u32 s44, s36, s62
	s_addc_u32 s45, s37, 0
	global_load_dwordx4 v[100:103], v12, s[44:45]
	global_load_dwordx4 v[104:107], v12, s[44:45] offset:16
	global_load_dwordx4 v[108:111], v13, s[44:45]
	global_load_dwordx4 v[112:115], v13, s[44:45] offset:16
	s_lshl_b32 s62, s29, 12
	s_add_u32 s48, s6, s62
	s_addc_u32 s49, s7, 0
	s_sub_u32 s66, s29, 1
	s_lshr_b32 s62, s66, 6
	s_lshl_b32 s62, s62, 2
	s_sub_u32 s63, s66, 0x2000
	s_lshr_b32 s63, s63, 4
	s_lshl_b32 s63, s63, 2
	s_add_u32 s63, s63, 0x200
	s_cmp_lt_u32 s66, 0x2000
	s_cselect_b32 s62, s62, s63
	s_add_u32 s63, s66, 2
	s_and_b32 s63, s63, 3
	s_add_u32 s62, s62, s63
	s_lshl_b32 s62, s62, 13
	s_add_u32 s46, s36, s62
	s_addc_u32 s47, s37, 0
	s_sub_u32 s66, s29, 2
	s_lshr_b32 s62, s66, 6
	s_lshl_b32 s62, s62, 2
	s_sub_u32 s63, s66, 0x2000
	s_lshr_b32 s63, s63, 4
	s_lshl_b32 s63, s63, 2
	s_add_u32 s63, s63, 0x200
	s_cmp_lt_u32 s66, 0x2000
	s_cselect_b32 s62, s62, s63
	s_add_u32 s63, s66, 2
	s_and_b32 s63, s63, 3
	s_add_u32 s62, s62, s63
	s_lshl_b32 s62, s62, 13
	s_add_u32 s50, s36, s62
	s_addc_u32 s51, s37, 0
	s_mov_b32 s67, 0
	s_mov_b32 s68, 0
	s_cmp_lt_u32 s29, 0x2010
	s_cbranch_scc0 .Lycx_samp
	s_cmp_lt_u32 s29, 1
	s_cselect_b32 s67, 1, 0
	s_cmp_lt_u32 s29, 2
	s_cselect_b32 s68, 1, 0
	s_branch .Lycx_ptrs
.Lycx_samp:
	s_sub_u32 s66, s29, 0x2010
	s_and_b32 s69, s66, 15
	s_lshr_b32 s66, s66, 4
	s_lshl_b32 s66, s66, 13
	s_add_u32 s72, s24, s66
	s_addc_u32 s73, s25, 0
	s_add_u32 s74, s72, 0x1000
	s_addc_u32 s75, s73, 0
	s_cmp_eq_u32 s69, 0
	s_cbranch_scc0 .Lycx_t1
	s_mov_b64 s[46:47], s[74:75]
	s_mov_b64 s[50:51], s[72:73]
	s_branch .Lycx_ptrs
.Lycx_t1:
	s_mov_b64 s[50:51], s[74:75]
.Lycx_ptrs:
	s_cmp_eq_u32 s67, 0
	s_cbranch_scc0 .Lycx_u1z
	global_load_dwordx4 v[116:119], v12, s[46:47]
	global_load_dwordx4 v[120:123], v12, s[46:47] offset:16
	s_branch .Lycx_u1d

.Lycx_u1d:
	s_cmp_eq_u32 s68, 0
	s_cbranch_scc0 .Lycx_u2z
	global_load_dwordx4 v[124:127], v12, s[50:51]
	global_load_dwordx4 v[128:131], v12, s[50:51] offset:16
	s_branch .Lycx_u2d
.Lycx_u2z:
	v_mov_b32_e32 v124, 0
	v_mov_b32_e32 v125, 0
	v_mov_b32_e32 v126, 0
	v_mov_b32_e32 v127, 0
	v_mov_b32_e32 v128, 0
	v_mov_b32_e32 v129, 0
	v_mov_b32_e32 v130, 0
	v_mov_b32_e32 v131, 0
.Lycx_u2d:
	s_waitcnt vmcnt(0)
	v_mul_f32_e32 v16, v132, v124
	v_mul_f32_e32 v17, v133, v125
	v_mul_f32_e32 v18, v134, v126
	v_mul_f32_e32 v19, v135, v127
	v_mul_f32_e32 v20, v136, v128
	v_mul_f32_e32 v21, v137, v129
	v_mul_f32_e32 v22, v138, v130
	v_mul_f32_e32 v23, v139, v131
	v_fmac_f32_e32 v16, v140, v116
	v_fmac_f32_e32 v17, v141, v117
	v_fmac_f32_e32 v18, v142, v118
	v_fmac_f32_e32 v19, v143, v119
	v_fmac_f32_e32 v20, v144, v120
	v_fmac_f32_e32 v21, v145, v121
	v_fmac_f32_e32 v22, v146, v122
	v_fmac_f32_e32 v23, v147, v123
	v_fmac_f32_e32 v16, v148, v100
	v_fmac_f32_e32 v17, v149, v101
	v_fmac_f32_e32 v18, v150, v102
	v_fmac_f32_e32 v19, v151, v103
	v_fmac_f32_e32 v20, v152, v104
	v_fmac_f32_e32 v21, v153, v105
	v_fmac_f32_e32 v22, v154, v106
	v_fmac_f32_e32 v23, v155, v107
	v_mul_f32_e32 v16, v108, v16
	v_mul_f32_e32 v17, v109, v17
	v_mul_f32_e32 v18, v110, v18
	v_mul_f32_e32 v19, v111, v19
	v_mul_f32_e32 v20, v112, v20
	v_mul_f32_e32 v21, v113, v21
	v_mul_f32_e32 v22, v114, v22
	v_mul_f32_e32 v23, v115, v23
	v_cvt_pk_bf16_f32 v40, v16, v17
	v_cvt_pk_bf16_f32 v41, v18, v19
	v_cvt_pk_bf16_f32 v42, v20, v21
	v_cvt_pk_bf16_f32 v43, v22, v23
	s_nop 0
	global_store_dwordx4 v14, v[40:43], s[48:49]
.Lycx_skip:
.LBB0_962:
	s_or_b64 exec, exec, s[8:9]
	v_readlane_b32 s2, v254, 54
	s_lshl_b32 s2, s2, 6
	s_lshl_b32 s3, s60, 13
	s_or_b32 s94, s3, s2
	s_lshl_b64 s[2:3], s[94:95], 2
	v_readlane_b32 s4, v252, 20
	s_add_u32 s90, s4, s2
	v_readlane_b32 s2, v252, 21
	s_addc_u32 s91, s2, s3
	s_lshl_b32 s2, s60, 16
	v_readlane_b32 s3, v252, 46
	s_or_b32 s94, s2, s3
	s_lshl_b64 s[2:3], s[94:95], 5
	v_writelane_b32 v255, s2, 11
	v_readlane_b32 s4, v254, 31
	v_readlane_b32 s5, v254, 32
	v_writelane_b32 v255, s3, 12
	s_lshl_b64 s[2:3], s[94:95], 10
	v_readlane_b32 s6, v254, 33
	s_or_b64 s[4:5], s[2:3], s[4:5]
	s_lshl_b64 s[2:3], s[60:61], 18
	v_readlane_b32 s7, v254, 34
	s_or_b64 s[6:7], s[2:3], s[6:7]
	s_mul_i32 s2, s60, 0x804000
	v_readlane_b32 s3, v252, 50
	s_or_b32 s8, s3, s2
	v_readlane_b32 s2, v254, 56
	v_writelane_b32 v255, s60, 5
	s_mul_i32 s94, s60, 0x88
	s_mov_b32 s9, s2
	s_lshl_b64 s[2:3], s[94:95], 2
	v_readlane_b32 s10, v252, 54
	s_add_u32 s2, s10, s2
	v_readlane_b32 s10, v252, 55
	s_addc_u32 s3, s10, s3
	v_readlane_b32 s10, v254, 42
	v_writelane_b32 v255, s61, 6
	s_add_u32 s10, s2, s10
	v_writelane_b32 v255, s10, 29
	s_addc_u32 s10, s3, 0
	v_writelane_b32 v255, s10, 15
	v_readlane_b32 s10, v254, 43
	s_add_u32 s2, s2, s10
	s_addc_u32 s3, s3, 0
	s_add_u32 s2, s2, 0x200
	v_writelane_b32 v255, s2, 17
	s_addc_u32 s2, s3, 0
	v_writelane_b32 v255, s2, 19
	s_lshl_b64 s[4:5], s[4:5], 2
	v_writelane_b32 v255, s4, 23
	s_mov_b32 s2, 0
	s_mov_b64 s[86:87], -1
	v_writelane_b32 v255, s5, 24
	s_lshl_b64 s[4:5], s[6:7], 2
	v_writelane_b32 v255, s4, 21
	s_nop 1
	v_writelane_b32 v255, s5, 22
	s_lshl_b64 s[4:5], s[8:9], 2
	v_writelane_b32 v255, s4, 25
	s_nop 1
	v_writelane_b32 v255, s5, 26
	s_branch .LBB0_966
